# previous best + P3 fused out-proj epilogue y_prompt stores written through (sc0 sc1)
# speedup vs baseline: 1.0034x; 1.0034x over previous
.LBB0_720:
	s_or_b64 exec, exec, s[2:3]
	s_lshl_b32 s0, s19, 5
	s_lshl_b32 s1, s10, 8
	s_or_b32 s0, s1, s0
	v_readlane_b32 s52, v248, 16
	v_and_or_b32 v130, v146, 12, s0
	v_readlane_b32 s64, v248, 28
	v_readlane_b32 s65, v248, 29
	s_lshl_b32 s0, s8, 8
	v_readlane_b32 s56, v248, 20
	v_readlane_b32 s57, v248, 21
	v_readlane_b32 s58, v248, 22
	v_readlane_b32 s59, v248, 23
	v_readlane_b32 s60, v248, 24
	v_readlane_b32 s61, v248, 25
	v_readlane_b32 s62, v248, 26
	v_readlane_b32 s63, v248, 27
	v_readlane_b32 s66, v248, 30
	v_readlane_b32 s67, v248, 31
	s_mov_b64 s[12:13], s[64:65]
	v_add_u32_e32 v152, s0, v148
	v_ashrrev_i32_e32 v131, 31, v130
	s_mov_b64 s[14:15], s[66:67]
	v_readlane_b32 s56, v248, 0
	v_add_u32_e32 v170, 16, v152
	v_add_u32_e32 v186, 32, v152
	v_add_u32_e32 v204, 48, v152
	v_lshlrev_b64 v[146:147], 2, v[130:131]
	v_readlane_b32 s57, v248, 1
	v_ashrrev_i32_e32 v153, 31, v152
	v_ashrrev_i32_e32 v171, 31, v170
	v_ashrrev_i32_e32 v187, 31, v186
	v_ashrrev_i32_e32 v205, 31, v204
	v_lshl_add_u64 v[150:151], s[56:57], 0, v[146:147]
	v_lshlrev_b64 v[154:155], 13, v[152:153]
	v_lshlrev_b64 v[170:171], 13, v[170:171]
	v_lshlrev_b64 v[186:187], 13, v[186:187]
	v_lshlrev_b64 v[204:205], 13, v[204:205]
	v_lshl_add_u64 v[130:131], s[12:13], 0, v[146:147]
	v_lshl_add_u64 v[166:167], v[150:151], 0, v[154:155]
	v_lshl_add_u64 v[182:183], v[150:151], 0, v[170:171]
	v_lshl_add_u64 v[200:201], v[150:151], 0, v[186:187]
	v_lshl_add_u64 v[216:217], v[150:151], 0, v[204:205]
	s_waitcnt lgkmcnt(0)
	s_waitcnt lgkmcnt(0)
	s_barrier
	global_load_dwordx4 v[142:145], v[130:131], off
	global_load_dwordx4 v[138:141], v[130:131], off offset:64
	global_load_dwordx4 v[134:137], v[130:131], off offset:512
	s_nop 0
	global_load_dwordx4 v[130:133], v[130:131], off offset:576
	s_nop 0
	global_load_dwordx4 v[154:157], v[166:167], off nt
	global_load_dwordx4 v[158:161], v[166:167], off offset:64 nt
	global_load_dwordx4 v[162:165], v[166:167], off offset:512 nt
	s_nop 0
	global_load_dwordx4 v[166:169], v[166:167], off offset:576 nt
	s_nop 0
	global_load_dwordx4 v[170:173], v[182:183], off nt
	global_load_dwordx4 v[174:177], v[182:183], off offset:64 nt
	global_load_dwordx4 v[178:181], v[182:183], off offset:512 nt
	s_nop 0
	global_load_dwordx4 v[182:185], v[182:183], off offset:576 nt
	s_nop 0
	global_load_dwordx4 v[186:189], v[200:201], off nt
	global_load_dwordx4 v[190:193], v[200:201], off offset:64 nt
	global_load_dwordx4 v[196:199], v[200:201], off offset:512 nt
	s_nop 0
	global_load_dwordx4 v[200:203], v[200:201], off offset:576 nt
	s_nop 0
	global_load_dwordx4 v[204:207], v[216:217], off nt
	global_load_dwordx4 v[208:211], v[216:217], off offset:64 nt
	global_load_dwordx4 v[212:215], v[216:217], off offset:512 nt
	s_nop 0
	global_load_dwordx4 v[216:219], v[216:217], off offset:576 nt
	v_lshl_add_u32 v148, v148, 2, 0
	v_add_u32_e32 v153, 0x1000, v148
	ds_read2_b32 v[220:221], v153 offset1:16
	ds_read2_b32 v[222:223], v153 offset0:32 offset1:48
	s_add_i32 s0, s0, s17
	v_readlane_b32 s53, v248, 17
	v_readlane_b32 s54, v248, 18
	v_readlane_b32 s55, v248, 19
	v_readlane_b32 s58, v248, 2
	v_readlane_b32 s59, v248, 3
	v_readlane_b32 s60, v248, 4
	v_readlane_b32 s61, v248, 5
	v_readlane_b32 s62, v248, 6
	v_readlane_b32 s63, v248, 7
	v_readlane_b32 s64, v248, 8
	v_readlane_b32 s65, v248, 9
	v_readlane_b32 s66, v248, 10
	v_readlane_b32 s67, v248, 11
	v_readlane_b32 s68, v248, 12
	v_readlane_b32 s69, v248, 13
	v_readlane_b32 s70, v248, 14
	v_readlane_b32 s71, v248, 15
	v_or_b32_e32 v148, s0, v1
	v_ashrrev_i32_e32 v149, 31, v148
	v_lshlrev_b64 v[224:225], 13, v[148:149]
	s_waitcnt lgkmcnt(1)
	v_pk_mul_f32 v[126:127], v[126:127], v[220:221] op_sel_hi:[1,0]
	v_pk_mul_f32 v[110:111], v[110:111], v[220:221] op_sel_hi:[1,0]
	s_waitcnt vmcnt(15)
	v_pk_fma_f32 v[126:127], v[142:143], v[126:127], v[154:155]
	v_lshl_add_u64 v[154:155], s[14:15], 0, v[224:225]
	v_pk_mul_f32 v[112:113], v[112:113], v[220:221] op_sel_hi:[1,0]
	v_lshl_add_u64 v[154:155], v[154:155], 0, v[146:147]
	s_waitcnt vmcnt(12)
	v_pk_fma_f32 v[112:113], v[132:133], v[112:113], v[168:169]
	v_pk_fma_f32 v[110:111], v[130:131], v[110:111], v[166:167]
	v_pk_mul_f32 v[118:119], v[118:119], v[220:221] op_sel_hi:[1,0]
	v_pk_mul_f32 v[120:121], v[120:121], v[220:221] op_sel_hi:[1,0]
	global_store_dwordx4 v[154:155], v[110:113], off offset:576 sc0 sc1
	v_pk_fma_f32 v[120:121], v[136:137], v[120:121], v[164:165]
	v_pk_fma_f32 v[118:119], v[134:135], v[118:119], v[162:163]
	v_or_b32_e32 v110, 16, v148
	v_ashrrev_i32_e32 v111, 31, v110
	global_store_dwordx4 v[154:155], v[118:121], off offset:512 sc0 sc1
	s_waitcnt lgkmcnt(0)
	v_pk_mul_f32 v[78:79], v[78:79], v[222:223] op_sel_hi:[1,0]
	v_pk_mul_f32 v[80:81], v[80:81], v[222:223] op_sel_hi:[1,0]
	v_lshlrev_b64 v[118:119], 13, v[110:111]
	v_mov_b32_e32 v120, v221
	v_pk_mul_f32 v[110:111], v[114:115], v[120:121] op_sel_hi:[1,0]
	v_lshl_add_u64 v[114:115], s[14:15], 0, v[118:119]
	v_pk_mul_f32 v[94:95], v[94:95], v[120:121] op_sel_hi:[1,0]
	v_pk_mul_f32 v[96:97], v[96:97], v[120:121] op_sel_hi:[1,0]
	v_lshl_add_u64 v[114:115], v[114:115], 0, v[146:147]
	s_waitcnt vmcnt(10)
	v_pk_fma_f32 v[96:97], v[132:133], v[96:97], v[184:185]
	v_pk_fma_f32 v[94:95], v[130:131], v[94:95], v[182:183]
	v_pk_mul_f32 v[102:103], v[102:103], v[120:121] op_sel_hi:[1,0]
	v_pk_mul_f32 v[104:105], v[104:105], v[120:121] op_sel_hi:[1,0]
	global_store_dwordx4 v[114:115], v[94:97], off offset:576 sc0 sc1
	v_pk_fma_f32 v[104:105], v[136:137], v[104:105], v[180:181]
	v_pk_fma_f32 v[102:103], v[134:135], v[102:103], v[178:179]
	v_or_b32_e32 v94, 32, v148
	v_ashrrev_i32_e32 v95, 31, v94
	global_store_dwordx4 v[114:115], v[102:105], off offset:512 sc0 sc1
	s_waitcnt vmcnt(8)
	v_pk_fma_f32 v[80:81], v[132:133], v[80:81], v[202:203]
	v_pk_fma_f32 v[78:79], v[130:131], v[78:79], v[200:201]
	v_lshlrev_b64 v[102:103], 13, v[94:95]
	v_pk_mul_f32 v[94:95], v[98:99], v[222:223] op_sel_hi:[1,0]
	v_lshl_add_u64 v[98:99], s[14:15], 0, v[102:103]
	v_lshl_add_u64 v[98:99], v[98:99], 0, v[146:147]
	v_pk_mul_f32 v[86:87], v[86:87], v[222:223] op_sel_hi:[1,0]
	v_pk_mul_f32 v[88:89], v[88:89], v[222:223] op_sel_hi:[1,0]
	global_store_dwordx4 v[98:99], v[78:81], off offset:576 sc0 sc1
	v_pk_fma_f32 v[88:89], v[136:137], v[88:89], v[198:199]
	v_pk_fma_f32 v[86:87], v[134:135], v[86:87], v[196:197]
	v_or_b32_e32 v78, 48, v148
	v_ashrrev_i32_e32 v79, 31, v78
	global_store_dwordx4 v[98:99], v[86:89], off offset:512 sc0 sc1
	v_pk_mul_f32 v[128:129], v[128:129], v[220:221] op_sel_hi:[1,0]
	v_pk_mul_f32 v[122:123], v[122:123], v[220:221] op_sel_hi:[1,0]
	v_lshlrev_b64 v[86:87], 13, v[78:79]
	v_mov_b32_e32 v88, v223
	v_pk_mul_f32 v[124:125], v[124:125], v[220:221] op_sel_hi:[1,0]
	v_pk_mul_f32 v[112:113], v[116:117], v[120:121] op_sel_hi:[1,0]
	v_pk_mul_f32 v[106:107], v[106:107], v[120:121] op_sel_hi:[1,0]
	v_pk_mul_f32 v[108:109], v[108:109], v[120:121] op_sel_hi:[1,0]
	v_pk_mul_f32 v[96:97], v[100:101], v[222:223] op_sel_hi:[1,0]
	v_pk_mul_f32 v[90:91], v[90:91], v[222:223] op_sel_hi:[1,0]
	v_pk_mul_f32 v[92:93], v[92:93], v[222:223] op_sel_hi:[1,0]
	v_pk_mul_f32 v[78:79], v[82:83], v[88:89] op_sel_hi:[1,0]
	v_pk_mul_f32 v[80:81], v[84:85], v[88:89] op_sel_hi:[1,0]
	v_lshl_add_u64 v[82:83], s[14:15], 0, v[86:87]
	v_pk_mul_f32 v[74:75], v[74:75], v[88:89] op_sel_hi:[1,0]
	v_pk_mul_f32 v[76:77], v[76:77], v[88:89] op_sel_hi:[1,0]
	v_pk_mul_f32 v[70:71], v[70:71], v[88:89] op_sel_hi:[1,0]
	v_pk_mul_f32 v[72:73], v[72:73], v[88:89] op_sel_hi:[1,0]
	v_pk_mul_f32 v[66:67], v[66:67], v[88:89] op_sel_hi:[1,0]
	v_pk_mul_f32 v[68:69], v[68:69], v[88:89] op_sel_hi:[1,0]
	v_pk_fma_f32 v[128:129], v[144:145], v[128:129], v[156:157]
	v_pk_fma_f32 v[124:125], v[140:141], v[124:125], v[160:161]
	v_pk_fma_f32 v[122:123], v[138:139], v[122:123], v[158:159]
	v_pk_fma_f32 v[112:113], v[144:145], v[112:113], v[172:173]
	v_pk_fma_f32 v[110:111], v[142:143], v[110:111], v[170:171]
	v_pk_fma_f32 v[108:109], v[140:141], v[108:109], v[176:177]
	v_pk_fma_f32 v[106:107], v[138:139], v[106:107], v[174:175]
	v_pk_fma_f32 v[96:97], v[144:145], v[96:97], v[188:189]
	v_pk_fma_f32 v[94:95], v[142:143], v[94:95], v[186:187]
	v_pk_fma_f32 v[92:93], v[140:141], v[92:93], v[192:193]
	v_pk_fma_f32 v[90:91], v[138:139], v[90:91], v[190:191]
	s_waitcnt vmcnt(9)
	v_pk_fma_f32 v[80:81], v[144:145], v[80:81], v[206:207]
	v_pk_fma_f32 v[78:79], v[142:143], v[78:79], v[204:205]
	v_lshl_add_u64 v[82:83], v[82:83], 0, v[146:147]
	s_waitcnt vmcnt(8)
	v_pk_fma_f32 v[76:77], v[140:141], v[76:77], v[210:211]
	v_pk_fma_f32 v[74:75], v[138:139], v[74:75], v[208:209]
	s_waitcnt vmcnt(7)
	v_pk_fma_f32 v[72:73], v[136:137], v[72:73], v[214:215]
	v_pk_fma_f32 v[70:71], v[134:135], v[70:71], v[212:213]
	s_waitcnt vmcnt(6)
	v_pk_fma_f32 v[68:69], v[132:133], v[68:69], v[218:219]
	v_pk_fma_f32 v[66:67], v[130:131], v[66:67], v[216:217]
	global_store_dwordx4 v[154:155], v[126:129], off sc0 sc1
	global_store_dwordx4 v[154:155], v[122:125], off offset:64 sc0 sc1
	global_store_dwordx4 v[114:115], v[110:113], off sc0 sc1
	global_store_dwordx4 v[114:115], v[106:109], off offset:64 sc0 sc1
	global_store_dwordx4 v[98:99], v[94:97], off sc0 sc1
	global_store_dwordx4 v[98:99], v[90:93], off offset:64 sc0 sc1
	global_store_dwordx4 v[82:83], v[78:81], off sc0 sc1
	global_store_dwordx4 v[82:83], v[74:77], off offset:64 sc0 sc1
	global_store_dwordx4 v[82:83], v[70:73], off offset:512 sc0 sc1
	global_store_dwordx4 v[82:83], v[66:69], off offset:576 sc0 sc1
	s_nop 1
	v_add_u32_e32 v66, 0x80, v152
	v_ashrrev_i32_e32 v67, 31, v66
	v_lshlrev_b64 v[66:67], 13, v[66:67]
	v_lshl_add_u64 v[82:83], v[150:151], 0, v[66:67]
	global_load_dwordx4 v[66:69], v[82:83], off nt
	global_load_dwordx4 v[70:73], v[82:83], off offset:64 nt
	global_load_dwordx4 v[74:77], v[82:83], off offset:512 nt
	global_load_dwordx4 v[78:81], v[82:83], off offset:576 nt
	v_add_u32_e32 v82, 0x90, v152
	v_ashrrev_i32_e32 v83, 31, v82
	v_lshlrev_b64 v[82:83], 13, v[82:83]
	v_lshl_add_u64 v[98:99], v[150:151], 0, v[82:83]
	global_load_dwordx4 v[82:85], v[98:99], off nt
	global_load_dwordx4 v[86:89], v[98:99], off offset:64 nt
	global_load_dwordx4 v[90:93], v[98:99], off offset:512 nt
	global_load_dwordx4 v[94:97], v[98:99], off offset:576 nt
	v_add_u32_e32 v98, 0xa0, v152
	v_add_u32_e32 v114, 0xb0, v152
	v_ashrrev_i32_e32 v99, 31, v98
	v_ashrrev_i32_e32 v115, 31, v114
	v_lshlrev_b64 v[98:99], 13, v[98:99]
	v_lshlrev_b64 v[114:115], 13, v[114:115]
	v_lshl_add_u64 v[110:111], v[150:151], 0, v[98:99]
	v_lshl_add_u64 v[126:127], v[150:151], 0, v[114:115]
	global_load_dwordx4 v[98:101], v[110:111], off nt
	global_load_dwordx4 v[102:105], v[110:111], off offset:64 nt
	global_load_dwordx4 v[106:109], v[110:111], off offset:512 nt
	s_nop 0
	global_load_dwordx4 v[110:113], v[110:111], off offset:576 nt
	s_nop 0
	global_load_dwordx4 v[114:117], v[126:127], off nt
	global_load_dwordx4 v[118:121], v[126:127], off offset:64 nt
	global_load_dwordx4 v[122:125], v[126:127], off offset:512 nt
	s_nop 0
	global_load_dwordx4 v[126:129], v[126:127], off offset:576 nt
	ds_read2_b32 v[150:151], v153 offset0:128 offset1:144
	ds_read2_b32 v[152:153], v153 offset0:160 offset1:176
	v_add_u32_e32 v154, 0x80, v148
	v_ashrrev_i32_e32 v155, 31, v154
	v_lshlrev_b64 v[154:155], 13, v[154:155]
	s_waitcnt lgkmcnt(1)
	v_pk_mul_f32 v[62:63], v[62:63], v[150:151] op_sel_hi:[1,0]
	v_pk_mul_f32 v[46:47], v[46:47], v[150:151] op_sel_hi:[1,0]
	s_waitcnt vmcnt(15)
	v_pk_fma_f32 v[62:63], v[142:143], v[62:63], v[66:67]
	v_lshl_add_u64 v[66:67], s[14:15], 0, v[154:155]
	v_pk_mul_f32 v[48:49], v[48:49], v[150:151] op_sel_hi:[1,0]
	v_lshl_add_u64 v[66:67], v[66:67], 0, v[146:147]
	s_waitcnt vmcnt(12)
	v_pk_fma_f32 v[48:49], v[132:133], v[48:49], v[80:81]
	v_pk_fma_f32 v[46:47], v[130:131], v[46:47], v[78:79]
	v_pk_mul_f32 v[54:55], v[54:55], v[150:151] op_sel_hi:[1,0]
	v_pk_mul_f32 v[56:57], v[56:57], v[150:151] op_sel_hi:[1,0]
	global_store_dwordx4 v[66:67], v[46:49], off offset:576 sc0 sc1
	v_pk_fma_f32 v[56:57], v[136:137], v[56:57], v[76:77]
	v_pk_fma_f32 v[54:55], v[134:135], v[54:55], v[74:75]
	v_add_u32_e32 v46, 0x90, v148
	v_ashrrev_i32_e32 v47, 31, v46
	global_store_dwordx4 v[66:67], v[54:57], off offset:512 sc0 sc1
	s_waitcnt lgkmcnt(0)
	v_pk_mul_f32 v[14:15], v[14:15], v[152:153] op_sel_hi:[1,0]
	v_pk_mul_f32 v[16:17], v[16:17], v[152:153] op_sel_hi:[1,0]
	v_lshlrev_b64 v[54:55], 13, v[46:47]
	v_mov_b32_e32 v56, v151
	v_pk_mul_f32 v[46:47], v[50:51], v[56:57] op_sel_hi:[1,0]
	v_lshl_add_u64 v[50:51], s[14:15], 0, v[54:55]
	v_pk_mul_f32 v[30:31], v[30:31], v[56:57] op_sel_hi:[1,0]
	v_pk_mul_f32 v[32:33], v[32:33], v[56:57] op_sel_hi:[1,0]
	v_lshl_add_u64 v[50:51], v[50:51], 0, v[146:147]
	s_waitcnt vmcnt(10)
	v_pk_fma_f32 v[32:33], v[132:133], v[32:33], v[96:97]
	v_pk_fma_f32 v[30:31], v[130:131], v[30:31], v[94:95]
	v_pk_mul_f32 v[38:39], v[38:39], v[56:57] op_sel_hi:[1,0]
	v_pk_mul_f32 v[40:41], v[40:41], v[56:57] op_sel_hi:[1,0]
	global_store_dwordx4 v[50:51], v[30:33], off offset:576 sc0 sc1
	v_pk_fma_f32 v[40:41], v[136:137], v[40:41], v[92:93]
	v_pk_fma_f32 v[38:39], v[134:135], v[38:39], v[90:91]
	v_add_u32_e32 v30, 0xa0, v148
	v_ashrrev_i32_e32 v31, 31, v30
	global_store_dwordx4 v[50:51], v[38:41], off offset:512 sc0 sc1
	s_waitcnt vmcnt(8)
	v_pk_fma_f32 v[16:17], v[132:133], v[16:17], v[112:113]
	v_pk_fma_f32 v[14:15], v[130:131], v[14:15], v[110:111]
	v_lshlrev_b64 v[38:39], 13, v[30:31]
	v_pk_mul_f32 v[30:31], v[34:35], v[152:153] op_sel_hi:[1,0]
	v_lshl_add_u64 v[34:35], s[14:15], 0, v[38:39]
	v_lshl_add_u64 v[34:35], v[34:35], 0, v[146:147]
	v_pk_mul_f32 v[22:23], v[22:23], v[152:153] op_sel_hi:[1,0]
	v_pk_mul_f32 v[24:25], v[24:25], v[152:153] op_sel_hi:[1,0]
	global_store_dwordx4 v[34:35], v[14:17], off offset:576 sc0 sc1
	v_pk_fma_f32 v[24:25], v[136:137], v[24:25], v[108:109]
	v_pk_fma_f32 v[22:23], v[134:135], v[22:23], v[106:107]
	v_add_u32_e32 v14, 0xb0, v148
	v_ashrrev_i32_e32 v15, 31, v14
	global_store_dwordx4 v[34:35], v[22:25], off offset:512 sc0 sc1
	v_pk_mul_f32 v[64:65], v[64:65], v[150:151] op_sel_hi:[1,0]
	v_pk_mul_f32 v[58:59], v[58:59], v[150:151] op_sel_hi:[1,0]
	v_lshlrev_b64 v[22:23], 13, v[14:15]
	v_mov_b32_e32 v24, v153
	v_pk_mul_f32 v[60:61], v[60:61], v[150:151] op_sel_hi:[1,0]
	v_pk_mul_f32 v[48:49], v[52:53], v[56:57] op_sel_hi:[1,0]
	v_pk_mul_f32 v[42:43], v[42:43], v[56:57] op_sel_hi:[1,0]
	v_pk_mul_f32 v[44:45], v[44:45], v[56:57] op_sel_hi:[1,0]
	v_pk_mul_f32 v[32:33], v[36:37], v[152:153] op_sel_hi:[1,0]
	v_pk_mul_f32 v[26:27], v[26:27], v[152:153] op_sel_hi:[1,0]
	v_pk_mul_f32 v[28:29], v[28:29], v[152:153] op_sel_hi:[1,0]
	v_pk_mul_f32 v[14:15], v[18:19], v[24:25] op_sel_hi:[1,0]
	v_pk_mul_f32 v[16:17], v[20:21], v[24:25] op_sel_hi:[1,0]
	v_lshl_add_u64 v[18:19], s[14:15], 0, v[22:23]
	v_pk_mul_f32 v[10:11], v[10:11], v[24:25] op_sel_hi:[1,0]
	v_pk_mul_f32 v[12:13], v[12:13], v[24:25] op_sel_hi:[1,0]
	v_pk_mul_f32 v[6:7], v[6:7], v[24:25] op_sel_hi:[1,0]
	v_pk_mul_f32 v[8:9], v[8:9], v[24:25] op_sel_hi:[1,0]
	v_pk_mul_f32 v[2:3], v[2:3], v[24:25] op_sel_hi:[1,0]
	v_pk_mul_f32 v[4:5], v[4:5], v[24:25] op_sel_hi:[1,0]
	v_pk_fma_f32 v[64:65], v[144:145], v[64:65], v[68:69]
	v_pk_fma_f32 v[60:61], v[140:141], v[60:61], v[72:73]
	v_pk_fma_f32 v[58:59], v[138:139], v[58:59], v[70:71]
	v_pk_fma_f32 v[48:49], v[144:145], v[48:49], v[84:85]
	v_pk_fma_f32 v[46:47], v[142:143], v[46:47], v[82:83]
	v_pk_fma_f32 v[44:45], v[140:141], v[44:45], v[88:89]
	v_pk_fma_f32 v[42:43], v[138:139], v[42:43], v[86:87]
	v_pk_fma_f32 v[32:33], v[144:145], v[32:33], v[100:101]
	v_pk_fma_f32 v[30:31], v[142:143], v[30:31], v[98:99]
	v_pk_fma_f32 v[28:29], v[140:141], v[28:29], v[104:105]
	v_pk_fma_f32 v[26:27], v[138:139], v[26:27], v[102:103]
	s_waitcnt vmcnt(9)
	v_pk_fma_f32 v[16:17], v[144:145], v[16:17], v[116:117]
	v_pk_fma_f32 v[14:15], v[142:143], v[14:15], v[114:115]
	v_lshl_add_u64 v[18:19], v[18:19], 0, v[146:147]
	s_waitcnt vmcnt(8)
	v_pk_fma_f32 v[12:13], v[140:141], v[12:13], v[120:121]
	v_pk_fma_f32 v[10:11], v[138:139], v[10:11], v[118:119]
	s_waitcnt vmcnt(7)
	v_pk_fma_f32 v[8:9], v[136:137], v[8:9], v[124:125]
	v_pk_fma_f32 v[6:7], v[134:135], v[6:7], v[122:123]
	s_waitcnt vmcnt(6)
	v_pk_fma_f32 v[4:5], v[132:133], v[4:5], v[128:129]
	v_pk_fma_f32 v[2:3], v[130:131], v[2:3], v[126:127]
	global_store_dwordx4 v[66:67], v[62:65], off sc0 sc1
	global_store_dwordx4 v[66:67], v[58:61], off offset:64 sc0 sc1
	global_store_dwordx4 v[50:51], v[46:49], off sc0 sc1
	global_store_dwordx4 v[50:51], v[42:45], off offset:64 sc0 sc1
	global_store_dwordx4 v[34:35], v[30:33], off sc0 sc1
	global_store_dwordx4 v[34:35], v[26:29], off offset:64 sc0 sc1
	global_store_dwordx4 v[18:19], v[14:17], off sc0 sc1
	global_store_dwordx4 v[18:19], v[10:13], off offset:64 sc0 sc1
	global_store_dwordx4 v[18:19], v[6:9], off offset:512 sc0 sc1
	global_store_dwordx4 v[18:19], v[2:5], off offset:576 sc0 sc1
